# branch GEMM: K-seam gate loads software-pipelined 8 deep, epilogue gate loads all in flight (were 48 serialized round trips per tile)
# speedup vs baseline: 1.0372x; 1.0205x over previous
.LBB0_214:
	s_cmpk_eq_i32 s50, 0x400
	s_cselect_b32 s1, 0, 0x400
	v_add_u32_e32 v172, s1, v171
	v_add_lshl_u32 v172, v172, v170, 1
	global_load_dwordx4 v[132:135], v172, s[4:5]
	global_load_dwordx4 v[136:139], v172, s[4:5] offset:2048
	global_load_dwordx4 v[190:193], v172, s[4:5] offset:256
	global_load_dwordx4 v[194:197], v172, s[4:5] offset:2304
	v_add_u32_e32 v172, 0x26000, v172
	global_load_dwordx4 v[198:201], v172, s[4:5]
	global_load_dwordx4 v[202:205], v172, s[4:5] offset:2048
	global_load_dwordx4 v[206:209], v172, s[4:5] offset:256
	global_load_dwordx4 v[210:213], v172, s[4:5] offset:2304
	v_add_u32_e32 v172, 0x26000, v172
	global_load_dwordx4 v[214:217], v172, s[4:5]
	global_load_dwordx4 v[218:221], v172, s[4:5] offset:2048
	global_load_dwordx4 v[222:225], v172, s[4:5] offset:256
	global_load_dwordx4 v[226:229], v172, s[4:5] offset:2304
	v_add_u32_e32 v172, 0x26000, v172
	global_load_dwordx4 v[230:233], v172, s[4:5]
	global_load_dwordx4 v[234:237], v172, s[4:5] offset:2048
	global_load_dwordx4 v[238:241], v172, s[4:5] offset:256
	global_load_dwordx4 v[242:245], v172, s[4:5] offset:2304
	s_waitcnt vmcnt(14)
	v_lshlrev_b32_e32 v250, 16, v136
	v_and_b32_e32 v251, 0xffff0000, v136
	v_rcp_f32_e32 v250, v250
	v_rcp_f32_e32 v251, v251
	v_lshlrev_b32_e32 v248, 16, v132
	v_and_b32_e32 v249, 0xffff0000, v132
	v_pk_mul_f32 v[250:251], v[250:251], v[248:249]
	v_pk_mul_f32 v[128:129], v[128:129], v[250:251]
	v_lshlrev_b32_e32 v246, 16, v137
	v_and_b32_e32 v247, 0xffff0000, v137
	v_rcp_f32_e32 v246, v246
	v_rcp_f32_e32 v247, v247
	v_lshlrev_b32_e32 v174, 16, v133
	v_and_b32_e32 v175, 0xffff0000, v133
	v_pk_mul_f32 v[246:247], v[246:247], v[174:175]
	v_pk_mul_f32 v[130:131], v[130:131], v[246:247]
	v_lshlrev_b32_e32 v250, 16, v138
	v_and_b32_e32 v251, 0xffff0000, v138
	v_rcp_f32_e32 v250, v250
	v_rcp_f32_e32 v251, v251
	v_lshlrev_b32_e32 v248, 16, v134
	v_and_b32_e32 v249, 0xffff0000, v134
	v_pk_mul_f32 v[250:251], v[250:251], v[248:249]
	v_pk_mul_f32 v[124:125], v[124:125], v[250:251]
	v_lshlrev_b32_e32 v246, 16, v139
	v_and_b32_e32 v247, 0xffff0000, v139
	v_rcp_f32_e32 v246, v246
	v_rcp_f32_e32 v247, v247
	v_lshlrev_b32_e32 v174, 16, v135
	v_and_b32_e32 v175, 0xffff0000, v135
	v_pk_mul_f32 v[246:247], v[246:247], v[174:175]
	v_pk_mul_f32 v[126:127], v[126:127], v[246:247]
	v_add_u32_e32 v172, 0xbe000, v172
	global_load_dwordx4 v[132:135], v172, s[4:5]
	global_load_dwordx4 v[136:139], v172, s[4:5] offset:2048
	s_waitcnt vmcnt(14)
	v_lshlrev_b32_e32 v250, 16, v194
	v_and_b32_e32 v251, 0xffff0000, v194
	v_rcp_f32_e32 v250, v250
	v_rcp_f32_e32 v251, v251
	v_lshlrev_b32_e32 v248, 16, v190
	v_and_b32_e32 v249, 0xffff0000, v190
	v_pk_mul_f32 v[250:251], v[250:251], v[248:249]
	v_pk_mul_f32 v[120:121], v[120:121], v[250:251]
	v_lshlrev_b32_e32 v246, 16, v195
	v_and_b32_e32 v247, 0xffff0000, v195
	v_rcp_f32_e32 v246, v246
	v_rcp_f32_e32 v247, v247
	v_lshlrev_b32_e32 v174, 16, v191
	v_and_b32_e32 v175, 0xffff0000, v191
	v_pk_mul_f32 v[246:247], v[246:247], v[174:175]
	v_pk_mul_f32 v[122:123], v[122:123], v[246:247]
	v_lshlrev_b32_e32 v250, 16, v196
	v_and_b32_e32 v251, 0xffff0000, v196
	v_rcp_f32_e32 v250, v250
	v_rcp_f32_e32 v251, v251
	v_lshlrev_b32_e32 v248, 16, v192
	v_and_b32_e32 v249, 0xffff0000, v192
	v_pk_mul_f32 v[250:251], v[250:251], v[248:249]
	v_pk_mul_f32 v[116:117], v[116:117], v[250:251]
	v_lshlrev_b32_e32 v246, 16, v197
	v_and_b32_e32 v247, 0xffff0000, v197
	v_rcp_f32_e32 v246, v246
	v_rcp_f32_e32 v247, v247
	v_lshlrev_b32_e32 v174, 16, v193
	v_and_b32_e32 v175, 0xffff0000, v193
	v_pk_mul_f32 v[246:247], v[246:247], v[174:175]
	v_pk_mul_f32 v[118:119], v[118:119], v[246:247]
	global_load_dwordx4 v[190:193], v172, s[4:5] offset:256
	global_load_dwordx4 v[194:197], v172, s[4:5] offset:2304
	s_waitcnt vmcnt(14)
	v_lshlrev_b32_e32 v250, 16, v202
	v_and_b32_e32 v251, 0xffff0000, v202
	v_rcp_f32_e32 v250, v250
	v_rcp_f32_e32 v251, v251
	v_lshlrev_b32_e32 v248, 16, v198
	v_and_b32_e32 v249, 0xffff0000, v198
	v_pk_mul_f32 v[250:251], v[250:251], v[248:249]
	v_pk_mul_f32 v[112:113], v[112:113], v[250:251]
	v_lshlrev_b32_e32 v246, 16, v203
	v_and_b32_e32 v247, 0xffff0000, v203
	v_rcp_f32_e32 v246, v246
	v_rcp_f32_e32 v247, v247
	v_lshlrev_b32_e32 v174, 16, v199
	v_and_b32_e32 v175, 0xffff0000, v199
	v_pk_mul_f32 v[246:247], v[246:247], v[174:175]
	v_pk_mul_f32 v[114:115], v[114:115], v[246:247]
	v_lshlrev_b32_e32 v250, 16, v204
	v_and_b32_e32 v251, 0xffff0000, v204
	v_rcp_f32_e32 v250, v250
	v_rcp_f32_e32 v251, v251
	v_lshlrev_b32_e32 v248, 16, v200
	v_and_b32_e32 v249, 0xffff0000, v200
	v_pk_mul_f32 v[250:251], v[250:251], v[248:249]
	v_pk_mul_f32 v[108:109], v[108:109], v[250:251]
	v_lshlrev_b32_e32 v246, 16, v205
	v_and_b32_e32 v247, 0xffff0000, v205
	v_rcp_f32_e32 v246, v246
	v_rcp_f32_e32 v247, v247
	v_lshlrev_b32_e32 v174, 16, v201
	v_and_b32_e32 v175, 0xffff0000, v201
	v_pk_mul_f32 v[246:247], v[246:247], v[174:175]
	v_pk_mul_f32 v[110:111], v[110:111], v[246:247]
	v_add_u32_e32 v172, 0x26000, v172
	global_load_dwordx4 v[198:201], v172, s[4:5]
	global_load_dwordx4 v[202:205], v172, s[4:5] offset:2048
	s_waitcnt vmcnt(14)
	v_lshlrev_b32_e32 v250, 16, v210
	v_and_b32_e32 v251, 0xffff0000, v210
	v_rcp_f32_e32 v250, v250
	v_rcp_f32_e32 v251, v251
	v_lshlrev_b32_e32 v248, 16, v206
	v_and_b32_e32 v249, 0xffff0000, v206
	v_pk_mul_f32 v[250:251], v[250:251], v[248:249]
	v_pk_mul_f32 v[104:105], v[104:105], v[250:251]
	v_lshlrev_b32_e32 v246, 16, v211
	v_and_b32_e32 v247, 0xffff0000, v211
	v_rcp_f32_e32 v246, v246
	v_rcp_f32_e32 v247, v247
	v_lshlrev_b32_e32 v174, 16, v207
	v_and_b32_e32 v175, 0xffff0000, v207
	v_pk_mul_f32 v[246:247], v[246:247], v[174:175]
	v_pk_mul_f32 v[106:107], v[106:107], v[246:247]
	v_lshlrev_b32_e32 v250, 16, v212
	v_and_b32_e32 v251, 0xffff0000, v212
	v_rcp_f32_e32 v250, v250
	v_rcp_f32_e32 v251, v251
	v_lshlrev_b32_e32 v248, 16, v208
	v_and_b32_e32 v249, 0xffff0000, v208
	v_pk_mul_f32 v[250:251], v[250:251], v[248:249]
	v_pk_mul_f32 v[100:101], v[100:101], v[250:251]
	v_lshlrev_b32_e32 v246, 16, v213
	v_and_b32_e32 v247, 0xffff0000, v213
	v_rcp_f32_e32 v246, v246
	v_rcp_f32_e32 v247, v247
	v_lshlrev_b32_e32 v174, 16, v209
	v_and_b32_e32 v175, 0xffff0000, v209
	v_pk_mul_f32 v[246:247], v[246:247], v[174:175]
	v_pk_mul_f32 v[102:103], v[102:103], v[246:247]
	global_load_dwordx4 v[206:209], v172, s[4:5] offset:256
	global_load_dwordx4 v[210:213], v172, s[4:5] offset:2304
	s_waitcnt vmcnt(14)
	v_lshlrev_b32_e32 v250, 16, v218
	v_and_b32_e32 v251, 0xffff0000, v218
	v_rcp_f32_e32 v250, v250
	v_rcp_f32_e32 v251, v251
	v_lshlrev_b32_e32 v248, 16, v214
	v_and_b32_e32 v249, 0xffff0000, v214
	v_pk_mul_f32 v[250:251], v[250:251], v[248:249]
	v_pk_mul_f32 v[96:97], v[96:97], v[250:251]
	v_lshlrev_b32_e32 v246, 16, v219
	v_and_b32_e32 v247, 0xffff0000, v219
	v_rcp_f32_e32 v246, v246
	v_rcp_f32_e32 v247, v247
	v_lshlrev_b32_e32 v174, 16, v215
	v_and_b32_e32 v175, 0xffff0000, v215
	v_pk_mul_f32 v[246:247], v[246:247], v[174:175]
	v_pk_mul_f32 v[98:99], v[98:99], v[246:247]
	v_lshlrev_b32_e32 v250, 16, v220
	v_and_b32_e32 v251, 0xffff0000, v220
	v_rcp_f32_e32 v250, v250
	v_rcp_f32_e32 v251, v251
	v_lshlrev_b32_e32 v248, 16, v216
	v_and_b32_e32 v249, 0xffff0000, v216
	v_pk_mul_f32 v[250:251], v[250:251], v[248:249]
	v_pk_mul_f32 v[92:93], v[92:93], v[250:251]
	v_lshlrev_b32_e32 v246, 16, v221
	v_and_b32_e32 v247, 0xffff0000, v221
	v_rcp_f32_e32 v246, v246
	v_rcp_f32_e32 v247, v247
	v_lshlrev_b32_e32 v174, 16, v217
	v_and_b32_e32 v175, 0xffff0000, v217
	v_pk_mul_f32 v[246:247], v[246:247], v[174:175]
	v_pk_mul_f32 v[94:95], v[94:95], v[246:247]
	v_add_u32_e32 v172, 0x26000, v172
	global_load_dwordx4 v[214:217], v172, s[4:5]
	global_load_dwordx4 v[218:221], v172, s[4:5] offset:2048
	s_waitcnt vmcnt(14)
	v_lshlrev_b32_e32 v250, 16, v226
	v_and_b32_e32 v251, 0xffff0000, v226
	v_rcp_f32_e32 v250, v250
	v_rcp_f32_e32 v251, v251
	v_lshlrev_b32_e32 v248, 16, v222
	v_and_b32_e32 v249, 0xffff0000, v222
	v_pk_mul_f32 v[250:251], v[250:251], v[248:249]
	v_pk_mul_f32 v[88:89], v[88:89], v[250:251]
	v_lshlrev_b32_e32 v246, 16, v227
	v_and_b32_e32 v247, 0xffff0000, v227
	v_rcp_f32_e32 v246, v246
	v_rcp_f32_e32 v247, v247
	v_lshlrev_b32_e32 v174, 16, v223
	v_and_b32_e32 v175, 0xffff0000, v223
	v_pk_mul_f32 v[246:247], v[246:247], v[174:175]
	v_pk_mul_f32 v[90:91], v[90:91], v[246:247]
	v_lshlrev_b32_e32 v250, 16, v228
	v_and_b32_e32 v251, 0xffff0000, v228
	v_rcp_f32_e32 v250, v250
	v_rcp_f32_e32 v251, v251
	v_lshlrev_b32_e32 v248, 16, v224
	v_and_b32_e32 v249, 0xffff0000, v224
	v_pk_mul_f32 v[250:251], v[250:251], v[248:249]
	v_pk_mul_f32 v[84:85], v[84:85], v[250:251]
	v_lshlrev_b32_e32 v246, 16, v229
	v_and_b32_e32 v247, 0xffff0000, v229
	v_rcp_f32_e32 v246, v246
	v_rcp_f32_e32 v247, v247
	v_lshlrev_b32_e32 v174, 16, v225
	v_and_b32_e32 v175, 0xffff0000, v225
	v_pk_mul_f32 v[246:247], v[246:247], v[174:175]
	v_pk_mul_f32 v[86:87], v[86:87], v[246:247]
	global_load_dwordx4 v[222:225], v172, s[4:5] offset:256
	global_load_dwordx4 v[226:229], v172, s[4:5] offset:2304
	s_waitcnt vmcnt(14)
	v_lshlrev_b32_e32 v250, 16, v234
	v_and_b32_e32 v251, 0xffff0000, v234
	v_rcp_f32_e32 v250, v250
	v_rcp_f32_e32 v251, v251
	v_lshlrev_b32_e32 v248, 16, v230
	v_and_b32_e32 v249, 0xffff0000, v230
	v_pk_mul_f32 v[250:251], v[250:251], v[248:249]
	v_pk_mul_f32 v[80:81], v[80:81], v[250:251]
	v_lshlrev_b32_e32 v246, 16, v235
	v_and_b32_e32 v247, 0xffff0000, v235
	v_rcp_f32_e32 v246, v246
	v_rcp_f32_e32 v247, v247
	v_lshlrev_b32_e32 v174, 16, v231
	v_and_b32_e32 v175, 0xffff0000, v231
	v_pk_mul_f32 v[246:247], v[246:247], v[174:175]
	v_pk_mul_f32 v[82:83], v[82:83], v[246:247]
	v_lshlrev_b32_e32 v250, 16, v236
	v_and_b32_e32 v251, 0xffff0000, v236
	v_rcp_f32_e32 v250, v250
	v_rcp_f32_e32 v251, v251
	v_lshlrev_b32_e32 v248, 16, v232
	v_and_b32_e32 v249, 0xffff0000, v232
	v_pk_mul_f32 v[250:251], v[250:251], v[248:249]
	v_pk_mul_f32 v[76:77], v[76:77], v[250:251]
	v_lshlrev_b32_e32 v246, 16, v237
	v_and_b32_e32 v247, 0xffff0000, v237
	v_rcp_f32_e32 v246, v246
	v_rcp_f32_e32 v247, v247
	v_lshlrev_b32_e32 v174, 16, v233
	v_and_b32_e32 v175, 0xffff0000, v233
	v_pk_mul_f32 v[246:247], v[246:247], v[174:175]
	v_pk_mul_f32 v[78:79], v[78:79], v[246:247]
	v_add_u32_e32 v172, 0x26000, v172
	global_load_dwordx4 v[230:233], v172, s[4:5]
	global_load_dwordx4 v[234:237], v172, s[4:5] offset:2048
	s_waitcnt vmcnt(14)
	v_lshlrev_b32_e32 v250, 16, v242
	v_and_b32_e32 v251, 0xffff0000, v242
	v_rcp_f32_e32 v250, v250
	v_rcp_f32_e32 v251, v251
	v_lshlrev_b32_e32 v248, 16, v238
	v_and_b32_e32 v249, 0xffff0000, v238
	v_pk_mul_f32 v[250:251], v[250:251], v[248:249]
	v_pk_mul_f32 v[72:73], v[72:73], v[250:251]
	v_lshlrev_b32_e32 v246, 16, v243
	v_and_b32_e32 v247, 0xffff0000, v243
	v_rcp_f32_e32 v246, v246
	v_rcp_f32_e32 v247, v247
	v_lshlrev_b32_e32 v174, 16, v239
	v_and_b32_e32 v175, 0xffff0000, v239
	v_pk_mul_f32 v[246:247], v[246:247], v[174:175]
	v_pk_mul_f32 v[74:75], v[74:75], v[246:247]
	v_lshlrev_b32_e32 v250, 16, v244
	v_and_b32_e32 v251, 0xffff0000, v244
	v_rcp_f32_e32 v250, v250
	v_rcp_f32_e32 v251, v251
	v_lshlrev_b32_e32 v248, 16, v240
	v_and_b32_e32 v249, 0xffff0000, v240
	v_pk_mul_f32 v[250:251], v[250:251], v[248:249]
	v_pk_mul_f32 v[68:69], v[68:69], v[250:251]
	v_lshlrev_b32_e32 v246, 16, v245
	v_and_b32_e32 v247, 0xffff0000, v245
	v_rcp_f32_e32 v246, v246
	v_rcp_f32_e32 v247, v247
	v_lshlrev_b32_e32 v174, 16, v241
	v_and_b32_e32 v175, 0xffff0000, v241
	v_pk_mul_f32 v[246:247], v[246:247], v[174:175]
	v_pk_mul_f32 v[70:71], v[70:71], v[246:247]
	global_load_dwordx4 v[238:241], v172, s[4:5] offset:256
	global_load_dwordx4 v[242:245], v172, s[4:5] offset:2304
	s_waitcnt vmcnt(14)
	v_lshlrev_b32_e32 v250, 16, v136
	v_and_b32_e32 v251, 0xffff0000, v136
	v_rcp_f32_e32 v250, v250
	v_rcp_f32_e32 v251, v251
	v_lshlrev_b32_e32 v248, 16, v132
	v_and_b32_e32 v249, 0xffff0000, v132
	v_pk_mul_f32 v[250:251], v[250:251], v[248:249]
	v_pk_mul_f32 v[64:65], v[64:65], v[250:251]
	v_lshlrev_b32_e32 v246, 16, v137
	v_and_b32_e32 v247, 0xffff0000, v137
	v_rcp_f32_e32 v246, v246
	v_rcp_f32_e32 v247, v247
	v_lshlrev_b32_e32 v174, 16, v133
	v_and_b32_e32 v175, 0xffff0000, v133
	v_pk_mul_f32 v[246:247], v[246:247], v[174:175]
	v_pk_mul_f32 v[66:67], v[66:67], v[246:247]
	v_lshlrev_b32_e32 v250, 16, v138
	v_and_b32_e32 v251, 0xffff0000, v138
	v_rcp_f32_e32 v250, v250
	v_rcp_f32_e32 v251, v251
	v_lshlrev_b32_e32 v248, 16, v134
	v_and_b32_e32 v249, 0xffff0000, v134
	v_pk_mul_f32 v[250:251], v[250:251], v[248:249]
	v_pk_mul_f32 v[60:61], v[60:61], v[250:251]
	v_lshlrev_b32_e32 v246, 16, v139
	v_and_b32_e32 v247, 0xffff0000, v139
	v_rcp_f32_e32 v246, v246
	v_rcp_f32_e32 v247, v247
	v_lshlrev_b32_e32 v174, 16, v135
	v_and_b32_e32 v175, 0xffff0000, v135
	v_pk_mul_f32 v[246:247], v[246:247], v[174:175]
	v_pk_mul_f32 v[62:63], v[62:63], v[246:247]
	s_waitcnt vmcnt(12)
	v_lshlrev_b32_e32 v250, 16, v194
	v_and_b32_e32 v251, 0xffff0000, v194
	v_rcp_f32_e32 v250, v250
	v_rcp_f32_e32 v251, v251
	v_lshlrev_b32_e32 v248, 16, v190
	v_and_b32_e32 v249, 0xffff0000, v190
	v_pk_mul_f32 v[250:251], v[250:251], v[248:249]
	v_pk_mul_f32 v[56:57], v[56:57], v[250:251]
	v_lshlrev_b32_e32 v246, 16, v195
	v_and_b32_e32 v247, 0xffff0000, v195
	v_rcp_f32_e32 v246, v246
	v_rcp_f32_e32 v247, v247
	v_lshlrev_b32_e32 v174, 16, v191
	v_and_b32_e32 v175, 0xffff0000, v191
	v_pk_mul_f32 v[246:247], v[246:247], v[174:175]
	v_pk_mul_f32 v[58:59], v[58:59], v[246:247]
	v_lshlrev_b32_e32 v250, 16, v196
	v_and_b32_e32 v251, 0xffff0000, v196
	v_rcp_f32_e32 v250, v250
	v_rcp_f32_e32 v251, v251
	v_lshlrev_b32_e32 v248, 16, v192
	v_and_b32_e32 v249, 0xffff0000, v192
	v_pk_mul_f32 v[250:251], v[250:251], v[248:249]
	v_pk_mul_f32 v[52:53], v[52:53], v[250:251]
	v_lshlrev_b32_e32 v246, 16, v197
	v_and_b32_e32 v247, 0xffff0000, v197
	v_rcp_f32_e32 v246, v246
	v_rcp_f32_e32 v247, v247
	v_lshlrev_b32_e32 v174, 16, v193
	v_and_b32_e32 v175, 0xffff0000, v193
	v_pk_mul_f32 v[246:247], v[246:247], v[174:175]
	v_pk_mul_f32 v[54:55], v[54:55], v[246:247]
	s_waitcnt vmcnt(10)
	v_lshlrev_b32_e32 v250, 16, v202
	v_and_b32_e32 v251, 0xffff0000, v202
	v_rcp_f32_e32 v250, v250
	v_rcp_f32_e32 v251, v251
	v_lshlrev_b32_e32 v248, 16, v198
	v_and_b32_e32 v249, 0xffff0000, v198
	v_pk_mul_f32 v[250:251], v[250:251], v[248:249]
	v_pk_mul_f32 v[48:49], v[48:49], v[250:251]
	v_lshlrev_b32_e32 v246, 16, v203
	v_and_b32_e32 v247, 0xffff0000, v203
	v_rcp_f32_e32 v246, v246
	v_rcp_f32_e32 v247, v247
	v_lshlrev_b32_e32 v174, 16, v199
	v_and_b32_e32 v175, 0xffff0000, v199
	v_pk_mul_f32 v[246:247], v[246:247], v[174:175]
	v_pk_mul_f32 v[50:51], v[50:51], v[246:247]
	v_lshlrev_b32_e32 v250, 16, v204
	v_and_b32_e32 v251, 0xffff0000, v204
	v_rcp_f32_e32 v250, v250
	v_rcp_f32_e32 v251, v251
	v_lshlrev_b32_e32 v248, 16, v200
	v_and_b32_e32 v249, 0xffff0000, v200
	v_pk_mul_f32 v[250:251], v[250:251], v[248:249]
	v_pk_mul_f32 v[44:45], v[44:45], v[250:251]
	v_lshlrev_b32_e32 v246, 16, v205
	v_and_b32_e32 v247, 0xffff0000, v205
	v_rcp_f32_e32 v246, v246
	v_rcp_f32_e32 v247, v247
	v_lshlrev_b32_e32 v174, 16, v201
	v_and_b32_e32 v175, 0xffff0000, v201
	v_pk_mul_f32 v[246:247], v[246:247], v[174:175]
	v_pk_mul_f32 v[46:47], v[46:47], v[246:247]
	s_waitcnt vmcnt(8)
	v_lshlrev_b32_e32 v250, 16, v210
	v_and_b32_e32 v251, 0xffff0000, v210
	v_rcp_f32_e32 v250, v250
	v_rcp_f32_e32 v251, v251
	v_lshlrev_b32_e32 v248, 16, v206
	v_and_b32_e32 v249, 0xffff0000, v206
	v_pk_mul_f32 v[250:251], v[250:251], v[248:249]
	v_pk_mul_f32 v[40:41], v[40:41], v[250:251]
	v_lshlrev_b32_e32 v246, 16, v211
	v_and_b32_e32 v247, 0xffff0000, v211
	v_rcp_f32_e32 v246, v246
	v_rcp_f32_e32 v247, v247
	v_lshlrev_b32_e32 v174, 16, v207
	v_and_b32_e32 v175, 0xffff0000, v207
	v_pk_mul_f32 v[246:247], v[246:247], v[174:175]
	v_pk_mul_f32 v[42:43], v[42:43], v[246:247]
	v_lshlrev_b32_e32 v250, 16, v212
	v_and_b32_e32 v251, 0xffff0000, v212
	v_rcp_f32_e32 v250, v250
	v_rcp_f32_e32 v251, v251
	v_lshlrev_b32_e32 v248, 16, v208
	v_and_b32_e32 v249, 0xffff0000, v208
	v_pk_mul_f32 v[250:251], v[250:251], v[248:249]
	v_pk_mul_f32 v[36:37], v[36:37], v[250:251]
	v_lshlrev_b32_e32 v246, 16, v213
	v_and_b32_e32 v247, 0xffff0000, v213
	v_rcp_f32_e32 v246, v246
	v_rcp_f32_e32 v247, v247
	v_lshlrev_b32_e32 v174, 16, v209
	v_and_b32_e32 v175, 0xffff0000, v209
	v_pk_mul_f32 v[246:247], v[246:247], v[174:175]
	v_pk_mul_f32 v[38:39], v[38:39], v[246:247]
	s_waitcnt vmcnt(6)
	v_lshlrev_b32_e32 v250, 16, v218
	v_and_b32_e32 v251, 0xffff0000, v218
	v_rcp_f32_e32 v250, v250
	v_rcp_f32_e32 v251, v251
	v_lshlrev_b32_e32 v248, 16, v214
	v_and_b32_e32 v249, 0xffff0000, v214
	v_pk_mul_f32 v[250:251], v[250:251], v[248:249]
	v_pk_mul_f32 v[32:33], v[32:33], v[250:251]
	v_lshlrev_b32_e32 v246, 16, v219
	v_and_b32_e32 v247, 0xffff0000, v219
	v_rcp_f32_e32 v246, v246
	v_rcp_f32_e32 v247, v247
	v_lshlrev_b32_e32 v174, 16, v215
	v_and_b32_e32 v175, 0xffff0000, v215
	v_pk_mul_f32 v[246:247], v[246:247], v[174:175]
	v_pk_mul_f32 v[34:35], v[34:35], v[246:247]
	v_lshlrev_b32_e32 v250, 16, v220
	v_and_b32_e32 v251, 0xffff0000, v220
	v_rcp_f32_e32 v250, v250
	v_rcp_f32_e32 v251, v251
	v_lshlrev_b32_e32 v248, 16, v216
	v_and_b32_e32 v249, 0xffff0000, v216
	v_pk_mul_f32 v[250:251], v[250:251], v[248:249]
	v_pk_mul_f32 v[28:29], v[28:29], v[250:251]
	v_lshlrev_b32_e32 v246, 16, v221
	v_and_b32_e32 v247, 0xffff0000, v221
	v_rcp_f32_e32 v246, v246
	v_rcp_f32_e32 v247, v247
	v_lshlrev_b32_e32 v174, 16, v217
	v_and_b32_e32 v175, 0xffff0000, v217
	v_pk_mul_f32 v[246:247], v[246:247], v[174:175]
	v_pk_mul_f32 v[30:31], v[30:31], v[246:247]
	s_waitcnt vmcnt(4)
	v_lshlrev_b32_e32 v250, 16, v226
	v_and_b32_e32 v251, 0xffff0000, v226
	v_rcp_f32_e32 v250, v250
	v_rcp_f32_e32 v251, v251
	v_lshlrev_b32_e32 v248, 16, v222
	v_and_b32_e32 v249, 0xffff0000, v222
	v_pk_mul_f32 v[250:251], v[250:251], v[248:249]
	v_pk_mul_f32 v[24:25], v[24:25], v[250:251]
	v_lshlrev_b32_e32 v246, 16, v227
	v_and_b32_e32 v247, 0xffff0000, v227
	v_rcp_f32_e32 v246, v246
	v_rcp_f32_e32 v247, v247
	v_lshlrev_b32_e32 v174, 16, v223
	v_and_b32_e32 v175, 0xffff0000, v223
	v_pk_mul_f32 v[246:247], v[246:247], v[174:175]
	v_pk_mul_f32 v[26:27], v[26:27], v[246:247]
	v_lshlrev_b32_e32 v250, 16, v228
	v_and_b32_e32 v251, 0xffff0000, v228
	v_rcp_f32_e32 v250, v250
	v_rcp_f32_e32 v251, v251
	v_lshlrev_b32_e32 v248, 16, v224
	v_and_b32_e32 v249, 0xffff0000, v224
	v_pk_mul_f32 v[250:251], v[250:251], v[248:249]
	v_pk_mul_f32 v[20:21], v[20:21], v[250:251]
	v_lshlrev_b32_e32 v246, 16, v229
	v_and_b32_e32 v247, 0xffff0000, v229
	v_rcp_f32_e32 v246, v246
	v_rcp_f32_e32 v247, v247
	v_lshlrev_b32_e32 v174, 16, v225
	v_and_b32_e32 v175, 0xffff0000, v225
	v_pk_mul_f32 v[246:247], v[246:247], v[174:175]
	v_pk_mul_f32 v[22:23], v[22:23], v[246:247]
	s_waitcnt vmcnt(2)
	v_lshlrev_b32_e32 v250, 16, v234
	v_and_b32_e32 v251, 0xffff0000, v234
	v_rcp_f32_e32 v250, v250
	v_rcp_f32_e32 v251, v251
	v_lshlrev_b32_e32 v248, 16, v230
	v_and_b32_e32 v249, 0xffff0000, v230
	v_pk_mul_f32 v[250:251], v[250:251], v[248:249]
	v_pk_mul_f32 v[16:17], v[16:17], v[250:251]
	v_lshlrev_b32_e32 v246, 16, v235
	v_and_b32_e32 v247, 0xffff0000, v235
	v_rcp_f32_e32 v246, v246
	v_rcp_f32_e32 v247, v247
	v_lshlrev_b32_e32 v174, 16, v231
	v_and_b32_e32 v175, 0xffff0000, v231
	v_pk_mul_f32 v[246:247], v[246:247], v[174:175]
	v_pk_mul_f32 v[18:19], v[18:19], v[246:247]
	v_lshlrev_b32_e32 v250, 16, v236
	v_and_b32_e32 v251, 0xffff0000, v236
	v_rcp_f32_e32 v250, v250
	v_rcp_f32_e32 v251, v251
	v_lshlrev_b32_e32 v248, 16, v232
	v_and_b32_e32 v249, 0xffff0000, v232
	v_pk_mul_f32 v[250:251], v[250:251], v[248:249]
	v_pk_mul_f32 v[12:13], v[12:13], v[250:251]
	v_lshlrev_b32_e32 v246, 16, v237
	v_and_b32_e32 v247, 0xffff0000, v237
	v_rcp_f32_e32 v246, v246
	v_rcp_f32_e32 v247, v247
	v_lshlrev_b32_e32 v174, 16, v233
	v_and_b32_e32 v175, 0xffff0000, v233
	v_pk_mul_f32 v[246:247], v[246:247], v[174:175]
	v_pk_mul_f32 v[14:15], v[14:15], v[246:247]
	s_waitcnt vmcnt(0)
	v_lshlrev_b32_e32 v250, 16, v242
	v_and_b32_e32 v251, 0xffff0000, v242
	v_rcp_f32_e32 v250, v250
	v_rcp_f32_e32 v251, v251
	v_lshlrev_b32_e32 v248, 16, v238
	v_and_b32_e32 v249, 0xffff0000, v238
	v_pk_mul_f32 v[250:251], v[250:251], v[248:249]
	v_pk_mul_f32 v[8:9], v[8:9], v[250:251]
	v_lshlrev_b32_e32 v246, 16, v243
	v_and_b32_e32 v247, 0xffff0000, v243
	v_rcp_f32_e32 v246, v246
	v_rcp_f32_e32 v247, v247
	v_lshlrev_b32_e32 v174, 16, v239
	v_and_b32_e32 v175, 0xffff0000, v239
	v_pk_mul_f32 v[246:247], v[246:247], v[174:175]
	v_pk_mul_f32 v[10:11], v[10:11], v[246:247]
	v_lshlrev_b32_e32 v250, 16, v244
	v_and_b32_e32 v251, 0xffff0000, v244
	v_rcp_f32_e32 v250, v250
	v_rcp_f32_e32 v251, v251
	v_lshlrev_b32_e32 v248, 16, v240
	v_and_b32_e32 v249, 0xffff0000, v240
	v_pk_mul_f32 v[250:251], v[250:251], v[248:249]
	v_pk_mul_f32 v[4:5], v[4:5], v[250:251]
	v_lshlrev_b32_e32 v246, 16, v245
	v_and_b32_e32 v247, 0xffff0000, v245
	v_rcp_f32_e32 v246, v246
	v_rcp_f32_e32 v247, v247
	v_lshlrev_b32_e32 v174, 16, v241
	v_and_b32_e32 v175, 0xffff0000, v241
	v_pk_mul_f32 v[246:247], v[246:247], v[174:175]
	v_pk_mul_f32 v[6:7], v[6:7], v[246:247]
	s_branch .LBB0_206

.LBB0_217:
	v_or_b32_e32 v173, s41, v165
	v_add_u32_e32 v172, 0xf00, v170
	v_add_lshl_u32 v172, v172, v173, 1
	v_lshlrev_b32_e32 v174, 11, v169
	v_lshl_add_u32 v174, v173, 1, v174
	s_andn2_b64 vcc, exec, s[38:39]
	s_mov_b64 s[10:11], -1
	global_load_dwordx4 v[132:135], v172, s[4:5]
	global_load_dwordx4 v[136:139], v172, s[4:5] offset:256
	v_add_u32_e32 v172, 0x26000, v172
	global_load_dwordx4 v[190:193], v172, s[4:5]
	global_load_dwordx4 v[194:197], v172, s[4:5] offset:256
	v_add_u32_e32 v172, 0x26000, v172
	global_load_dwordx4 v[198:201], v172, s[4:5]
	global_load_dwordx4 v[202:205], v172, s[4:5] offset:256
	v_add_u32_e32 v172, 0x26000, v172
	global_load_dwordx4 v[206:209], v172, s[4:5]
	global_load_dwordx4 v[210:213], v172, s[4:5] offset:256
	v_add_u32_e32 v172, 0xbe000, v172
	global_load_dwordx4 v[214:217], v172, s[4:5]
	global_load_dwordx4 v[218:221], v172, s[4:5] offset:256
	v_add_u32_e32 v172, 0x26000, v172
	global_load_dwordx4 v[222:225], v172, s[4:5]
	global_load_dwordx4 v[226:229], v172, s[4:5] offset:256
	v_add_u32_e32 v172, 0x26000, v172
	global_load_dwordx4 v[230:233], v172, s[4:5]
	global_load_dwordx4 v[234:237], v172, s[4:5] offset:256
	v_add_u32_e32 v172, 0x26000, v172
	global_load_dwordx4 v[238:241], v172, s[4:5]
	global_load_dwordx4 v[242:245], v172, s[4:5] offset:256
	s_waitcnt vmcnt(15)
	v_lshlrev_b32_e32 v246, 16, v132
	v_and_b32_e32 v247, 0xffff0000, v132
	v_lshlrev_b32_e32 v248, 16, v133
	v_and_b32_e32 v249, 0xffff0000, v133
	v_lshlrev_b32_e32 v250, 16, v134
	v_and_b32_e32 v251, 0xffff0000, v134
	v_lshlrev_b32_e32 v152, 16, v135
	v_and_b32_e32 v153, 0xffff0000, v135
	v_pk_mul_f32 v[128:129], v[128:129], v[246:247]
	v_pk_mul_f32 v[130:131], v[130:131], v[248:249]
	v_pk_mul_f32 v[124:125], v[124:125], v[250:251]
	v_pk_mul_f32 v[126:127], v[126:127], v[152:153]
	v_cvt_pk_bf16_f32 v128, v128, v129
	v_cvt_pk_bf16_f32 v129, v130, v131
	v_cvt_pk_bf16_f32 v130, v124, v125
	v_cvt_pk_bf16_f32 v131, v126, v127
	global_store_dwordx4 v174, v[128:131], s[2:3]
	s_waitcnt vmcnt(15)
	v_lshlrev_b32_e32 v246, 16, v136
	v_and_b32_e32 v247, 0xffff0000, v136
	v_lshlrev_b32_e32 v248, 16, v137
	v_and_b32_e32 v249, 0xffff0000, v137
	v_lshlrev_b32_e32 v250, 16, v138
	v_and_b32_e32 v251, 0xffff0000, v138
	v_lshlrev_b32_e32 v152, 16, v139
	v_and_b32_e32 v153, 0xffff0000, v139
	v_pk_mul_f32 v[120:121], v[120:121], v[246:247]
	v_pk_mul_f32 v[122:123], v[122:123], v[248:249]
	v_pk_mul_f32 v[116:117], v[116:117], v[250:251]
	v_pk_mul_f32 v[118:119], v[118:119], v[152:153]
	v_cvt_pk_bf16_f32 v120, v120, v121
	v_cvt_pk_bf16_f32 v121, v122, v123
	v_cvt_pk_bf16_f32 v122, v116, v117
	v_cvt_pk_bf16_f32 v123, v118, v119
	global_store_dwordx4 v174, v[120:123], s[2:3] offset:256
	v_add_u32_e32 v174, 0x8000, v174
	s_waitcnt vmcnt(15)
	v_lshlrev_b32_e32 v246, 16, v190
	v_and_b32_e32 v247, 0xffff0000, v190
	v_lshlrev_b32_e32 v248, 16, v191
	v_and_b32_e32 v249, 0xffff0000, v191
	v_lshlrev_b32_e32 v250, 16, v192
	v_and_b32_e32 v251, 0xffff0000, v192
	v_lshlrev_b32_e32 v152, 16, v193
	v_and_b32_e32 v153, 0xffff0000, v193
	v_pk_mul_f32 v[112:113], v[112:113], v[246:247]
	v_pk_mul_f32 v[114:115], v[114:115], v[248:249]
	v_pk_mul_f32 v[108:109], v[108:109], v[250:251]
	v_pk_mul_f32 v[110:111], v[110:111], v[152:153]
	v_cvt_pk_bf16_f32 v112, v112, v113
	v_cvt_pk_bf16_f32 v113, v114, v115
	v_cvt_pk_bf16_f32 v114, v108, v109
	v_cvt_pk_bf16_f32 v115, v110, v111
	global_store_dwordx4 v174, v[112:115], s[2:3]
	s_waitcnt vmcnt(15)
	v_lshlrev_b32_e32 v246, 16, v194
	v_and_b32_e32 v247, 0xffff0000, v194
	v_lshlrev_b32_e32 v248, 16, v195
	v_and_b32_e32 v249, 0xffff0000, v195
	v_lshlrev_b32_e32 v250, 16, v196
	v_and_b32_e32 v251, 0xffff0000, v196
	v_lshlrev_b32_e32 v152, 16, v197
	v_and_b32_e32 v153, 0xffff0000, v197
	v_pk_mul_f32 v[104:105], v[104:105], v[246:247]
	v_pk_mul_f32 v[106:107], v[106:107], v[248:249]
	v_pk_mul_f32 v[100:101], v[100:101], v[250:251]
	v_pk_mul_f32 v[102:103], v[102:103], v[152:153]
	v_cvt_pk_bf16_f32 v104, v104, v105
	v_cvt_pk_bf16_f32 v105, v106, v107
	v_cvt_pk_bf16_f32 v106, v100, v101
	v_cvt_pk_bf16_f32 v107, v102, v103
	global_store_dwordx4 v174, v[104:107], s[2:3] offset:256
	v_add_u32_e32 v174, 0x8000, v174
	s_waitcnt vmcnt(15)
	v_lshlrev_b32_e32 v246, 16, v198
	v_and_b32_e32 v247, 0xffff0000, v198
	v_lshlrev_b32_e32 v248, 16, v199
	v_and_b32_e32 v249, 0xffff0000, v199
	v_lshlrev_b32_e32 v250, 16, v200
	v_and_b32_e32 v251, 0xffff0000, v200
	v_lshlrev_b32_e32 v152, 16, v201
	v_and_b32_e32 v153, 0xffff0000, v201
	v_pk_mul_f32 v[96:97], v[96:97], v[246:247]
	v_pk_mul_f32 v[98:99], v[98:99], v[248:249]
	v_pk_mul_f32 v[92:93], v[92:93], v[250:251]
	v_pk_mul_f32 v[94:95], v[94:95], v[152:153]
	v_cvt_pk_bf16_f32 v96, v96, v97
	v_cvt_pk_bf16_f32 v97, v98, v99
	v_cvt_pk_bf16_f32 v98, v92, v93
	v_cvt_pk_bf16_f32 v99, v94, v95
	global_store_dwordx4 v174, v[96:99], s[2:3]
	s_waitcnt vmcnt(15)
	v_lshlrev_b32_e32 v246, 16, v202
	v_and_b32_e32 v247, 0xffff0000, v202
	v_lshlrev_b32_e32 v248, 16, v203
	v_and_b32_e32 v249, 0xffff0000, v203
	v_lshlrev_b32_e32 v250, 16, v204
	v_and_b32_e32 v251, 0xffff0000, v204
	v_lshlrev_b32_e32 v152, 16, v205
	v_and_b32_e32 v153, 0xffff0000, v205
	v_pk_mul_f32 v[88:89], v[88:89], v[246:247]
	v_pk_mul_f32 v[90:91], v[90:91], v[248:249]
	v_pk_mul_f32 v[84:85], v[84:85], v[250:251]
	v_pk_mul_f32 v[86:87], v[86:87], v[152:153]
	v_cvt_pk_bf16_f32 v88, v88, v89
	v_cvt_pk_bf16_f32 v89, v90, v91
	v_cvt_pk_bf16_f32 v90, v84, v85
	v_cvt_pk_bf16_f32 v91, v86, v87
	global_store_dwordx4 v174, v[88:91], s[2:3] offset:256
	v_add_u32_e32 v174, 0x8000, v174
	s_waitcnt vmcnt(15)
	v_lshlrev_b32_e32 v246, 16, v206
	v_and_b32_e32 v247, 0xffff0000, v206
	v_lshlrev_b32_e32 v248, 16, v207
	v_and_b32_e32 v249, 0xffff0000, v207
	v_lshlrev_b32_e32 v250, 16, v208
	v_and_b32_e32 v251, 0xffff0000, v208
	v_lshlrev_b32_e32 v152, 16, v209
	v_and_b32_e32 v153, 0xffff0000, v209
	v_pk_mul_f32 v[80:81], v[80:81], v[246:247]
	v_pk_mul_f32 v[82:83], v[82:83], v[248:249]
	v_pk_mul_f32 v[76:77], v[76:77], v[250:251]
	v_pk_mul_f32 v[78:79], v[78:79], v[152:153]
	v_cvt_pk_bf16_f32 v80, v80, v81
	v_cvt_pk_bf16_f32 v81, v82, v83
	v_cvt_pk_bf16_f32 v82, v76, v77
	v_cvt_pk_bf16_f32 v83, v78, v79
	global_store_dwordx4 v174, v[80:83], s[2:3]
	s_waitcnt vmcnt(15)
	v_lshlrev_b32_e32 v246, 16, v210
	v_and_b32_e32 v247, 0xffff0000, v210
	v_lshlrev_b32_e32 v248, 16, v211
	v_and_b32_e32 v249, 0xffff0000, v211
	v_lshlrev_b32_e32 v250, 16, v212
	v_and_b32_e32 v251, 0xffff0000, v212
	v_lshlrev_b32_e32 v152, 16, v213
	v_and_b32_e32 v153, 0xffff0000, v213
	v_pk_mul_f32 v[72:73], v[72:73], v[246:247]
	v_pk_mul_f32 v[74:75], v[74:75], v[248:249]
	v_pk_mul_f32 v[68:69], v[68:69], v[250:251]
	v_pk_mul_f32 v[70:71], v[70:71], v[152:153]
	v_cvt_pk_bf16_f32 v72, v72, v73
	v_cvt_pk_bf16_f32 v73, v74, v75
	v_cvt_pk_bf16_f32 v74, v68, v69
	v_cvt_pk_bf16_f32 v75, v70, v71
	global_store_dwordx4 v174, v[72:75], s[2:3] offset:256
	v_add_u32_e32 v174, 0x28000, v174
	s_waitcnt vmcnt(15)
	v_lshlrev_b32_e32 v246, 16, v214
	v_and_b32_e32 v247, 0xffff0000, v214
	v_lshlrev_b32_e32 v248, 16, v215
	v_and_b32_e32 v249, 0xffff0000, v215
	v_lshlrev_b32_e32 v250, 16, v216
	v_and_b32_e32 v251, 0xffff0000, v216
	v_lshlrev_b32_e32 v152, 16, v217
	v_and_b32_e32 v153, 0xffff0000, v217
	v_pk_mul_f32 v[64:65], v[64:65], v[246:247]
	v_pk_mul_f32 v[66:67], v[66:67], v[248:249]
	v_pk_mul_f32 v[60:61], v[60:61], v[250:251]
	v_pk_mul_f32 v[62:63], v[62:63], v[152:153]
	v_cvt_pk_bf16_f32 v64, v64, v65
	v_cvt_pk_bf16_f32 v65, v66, v67
	v_cvt_pk_bf16_f32 v66, v60, v61
	v_cvt_pk_bf16_f32 v67, v62, v63
	global_store_dwordx4 v174, v[64:67], s[2:3]
	s_waitcnt vmcnt(15)
	v_lshlrev_b32_e32 v246, 16, v218
	v_and_b32_e32 v247, 0xffff0000, v218
	v_lshlrev_b32_e32 v248, 16, v219
	v_and_b32_e32 v249, 0xffff0000, v219
	v_lshlrev_b32_e32 v250, 16, v220
	v_and_b32_e32 v251, 0xffff0000, v220
	v_lshlrev_b32_e32 v152, 16, v221
	v_and_b32_e32 v153, 0xffff0000, v221
	v_pk_mul_f32 v[56:57], v[56:57], v[246:247]
	v_pk_mul_f32 v[58:59], v[58:59], v[248:249]
	v_pk_mul_f32 v[52:53], v[52:53], v[250:251]
	v_pk_mul_f32 v[54:55], v[54:55], v[152:153]
	v_cvt_pk_bf16_f32 v56, v56, v57
	v_cvt_pk_bf16_f32 v57, v58, v59
	v_cvt_pk_bf16_f32 v58, v52, v53
	v_cvt_pk_bf16_f32 v59, v54, v55
	global_store_dwordx4 v174, v[56:59], s[2:3] offset:256
	v_add_u32_e32 v174, 0x8000, v174
	s_waitcnt vmcnt(15)
	v_lshlrev_b32_e32 v246, 16, v222
	v_and_b32_e32 v247, 0xffff0000, v222
	v_lshlrev_b32_e32 v248, 16, v223
	v_and_b32_e32 v249, 0xffff0000, v223
	v_lshlrev_b32_e32 v250, 16, v224
	v_and_b32_e32 v251, 0xffff0000, v224
	v_lshlrev_b32_e32 v152, 16, v225
	v_and_b32_e32 v153, 0xffff0000, v225
	v_pk_mul_f32 v[48:49], v[48:49], v[246:247]
	v_pk_mul_f32 v[50:51], v[50:51], v[248:249]
	v_pk_mul_f32 v[44:45], v[44:45], v[250:251]
	v_pk_mul_f32 v[46:47], v[46:47], v[152:153]
	v_cvt_pk_bf16_f32 v48, v48, v49
	v_cvt_pk_bf16_f32 v49, v50, v51
	v_cvt_pk_bf16_f32 v50, v44, v45
	v_cvt_pk_bf16_f32 v51, v46, v47
	global_store_dwordx4 v174, v[48:51], s[2:3]
	s_waitcnt vmcnt(15)
	v_lshlrev_b32_e32 v246, 16, v226
	v_and_b32_e32 v247, 0xffff0000, v226
	v_lshlrev_b32_e32 v248, 16, v227
	v_and_b32_e32 v249, 0xffff0000, v227
	v_lshlrev_b32_e32 v250, 16, v228
	v_and_b32_e32 v251, 0xffff0000, v228
	v_lshlrev_b32_e32 v152, 16, v229
	v_and_b32_e32 v153, 0xffff0000, v229
	v_pk_mul_f32 v[40:41], v[40:41], v[246:247]
	v_pk_mul_f32 v[42:43], v[42:43], v[248:249]
	v_pk_mul_f32 v[36:37], v[36:37], v[250:251]
	v_pk_mul_f32 v[38:39], v[38:39], v[152:153]
	v_cvt_pk_bf16_f32 v40, v40, v41
	v_cvt_pk_bf16_f32 v41, v42, v43
	v_cvt_pk_bf16_f32 v42, v36, v37
	v_cvt_pk_bf16_f32 v43, v38, v39
	global_store_dwordx4 v174, v[40:43], s[2:3] offset:256
	v_add_u32_e32 v174, 0x8000, v174
	s_waitcnt vmcnt(15)
	v_lshlrev_b32_e32 v246, 16, v230
	v_and_b32_e32 v247, 0xffff0000, v230
	v_lshlrev_b32_e32 v248, 16, v231
	v_and_b32_e32 v249, 0xffff0000, v231
	v_lshlrev_b32_e32 v250, 16, v232
	v_and_b32_e32 v251, 0xffff0000, v232
	v_lshlrev_b32_e32 v152, 16, v233
	v_and_b32_e32 v153, 0xffff0000, v233
	v_pk_mul_f32 v[32:33], v[32:33], v[246:247]
	v_pk_mul_f32 v[34:35], v[34:35], v[248:249]
	v_pk_mul_f32 v[28:29], v[28:29], v[250:251]
	v_pk_mul_f32 v[30:31], v[30:31], v[152:153]
	v_cvt_pk_bf16_f32 v32, v32, v33
	v_cvt_pk_bf16_f32 v33, v34, v35
	v_cvt_pk_bf16_f32 v34, v28, v29
	v_cvt_pk_bf16_f32 v35, v30, v31
	global_store_dwordx4 v174, v[32:35], s[2:3]
	s_waitcnt vmcnt(15)
	v_lshlrev_b32_e32 v246, 16, v234
	v_and_b32_e32 v247, 0xffff0000, v234
	v_lshlrev_b32_e32 v248, 16, v235
	v_and_b32_e32 v249, 0xffff0000, v235
	v_lshlrev_b32_e32 v250, 16, v236
	v_and_b32_e32 v251, 0xffff0000, v236
	v_lshlrev_b32_e32 v152, 16, v237
	v_and_b32_e32 v153, 0xffff0000, v237
	v_pk_mul_f32 v[24:25], v[24:25], v[246:247]
	v_pk_mul_f32 v[26:27], v[26:27], v[248:249]
	v_pk_mul_f32 v[20:21], v[20:21], v[250:251]
	v_pk_mul_f32 v[22:23], v[22:23], v[152:153]
	v_cvt_pk_bf16_f32 v24, v24, v25
	v_cvt_pk_bf16_f32 v25, v26, v27
	v_cvt_pk_bf16_f32 v26, v20, v21
	v_cvt_pk_bf16_f32 v27, v22, v23
	global_store_dwordx4 v174, v[24:27], s[2:3] offset:256
	v_add_u32_e32 v174, 0x8000, v174
	s_waitcnt vmcnt(15)
	v_lshlrev_b32_e32 v246, 16, v238
	v_and_b32_e32 v247, 0xffff0000, v238
	v_lshlrev_b32_e32 v248, 16, v239
	v_and_b32_e32 v249, 0xffff0000, v239
	v_lshlrev_b32_e32 v250, 16, v240
	v_and_b32_e32 v251, 0xffff0000, v240
	v_lshlrev_b32_e32 v152, 16, v241
	v_and_b32_e32 v153, 0xffff0000, v241
	v_pk_mul_f32 v[16:17], v[16:17], v[246:247]
	v_pk_mul_f32 v[18:19], v[18:19], v[248:249]
	v_pk_mul_f32 v[12:13], v[12:13], v[250:251]
	v_pk_mul_f32 v[14:15], v[14:15], v[152:153]
	v_cvt_pk_bf16_f32 v16, v16, v17
	v_cvt_pk_bf16_f32 v17, v18, v19
	v_cvt_pk_bf16_f32 v18, v12, v13
	v_cvt_pk_bf16_f32 v19, v14, v15
	global_store_dwordx4 v174, v[16:19], s[2:3]
	s_waitcnt vmcnt(15)
	v_lshlrev_b32_e32 v246, 16, v242
	v_and_b32_e32 v247, 0xffff0000, v242
	v_lshlrev_b32_e32 v248, 16, v243
	v_and_b32_e32 v249, 0xffff0000, v243
	v_lshlrev_b32_e32 v250, 16, v244
	v_and_b32_e32 v251, 0xffff0000, v244
	v_lshlrev_b32_e32 v152, 16, v245
	v_and_b32_e32 v153, 0xffff0000, v245
	v_pk_mul_f32 v[8:9], v[8:9], v[246:247]
	v_pk_mul_f32 v[10:11], v[10:11], v[248:249]
	v_pk_mul_f32 v[4:5], v[4:5], v[250:251]
	v_pk_mul_f32 v[6:7], v[6:7], v[152:153]
	v_cvt_pk_bf16_f32 v8, v8, v9
	v_cvt_pk_bf16_f32 v9, v10, v11
	v_cvt_pk_bf16_f32 v10, v4, v5
	v_cvt_pk_bf16_f32 v11, v6, v7
	global_store_dwordx4 v174, v[8:11], s[2:3] offset:256
	s_cbranch_vccnz .LBB0_198
	s_andn2_b64 vcc, exec, s[36:37]
	s_cbranch_vccnz .LBB0_197
	s_barrier
	s_branch .LBB0_197
